# mem-q GEMM rebalanced: 4 half units (256x128) on all 4 panel members instead of 2 full units on 2
# speedup vs baseline: 1.0135x; 1.0007x over previous
.LBB0_814:
	s_andn2_b64 vcc, exec, s[10:11]
	s_cbranch_vccnz .LBB0_821
	s_cmp_gt_i32 s16, 3
	s_mov_b64 s[12:13], -1
	s_cbranch_scc0 .LBB0_819
	v_readlane_b32 s4, v253, 22
	s_mov_b64 s[12:13], 0
	s_cmp_gt_i32 s4, 3
	s_mov_b64 s[8:9], 0
	v_readlane_b32 s5, v253, 23
	s_cbranch_scc1 .LBB0_818
	s_mul_i32 s4, s19, 0x2600000
	s_ashr_i32 s5, s4, 31
	s_add_u32 s6, s82, s4
	s_addc_u32 s7, s83, s5
	v_readlane_b32 s4, v253, 22
	v_readlane_b32 s5, v253, 23
	s_mov_b32 s8, s4
	s_ashr_i32 s9, s4, 31
	v_writelane_b32 v253, s4, 22
	s_mov_b32 s44, 16
	s_movk_i32 s40, 0x800
	v_writelane_b32 v253, s5, 23
	s_lshl_b64 s[4:5], s[8:9], 18
	s_add_u32 s4, s6, s4
	s_addc_u32 s5, s7, s5
	s_add_u32 s6, s4, 0x1280000
	s_addc_u32 s7, s5, 0
	s_mov_b64 s[8:9], -1

.LBB0_851:
	s_andn2_b64 vcc, exec, s[8:9]
	s_cbranch_vccnz .LBB0_993
	v_ashrrev_i32_e32 v2, 31, v14
	v_lshrrev_b32_e32 v2, 26, v2
	v_add_u32_e32 v2, v14, v2
	v_ashrrev_i32_e32 v15, 6, v2
	v_bfe_i32 v2, v14, 27, 1
	v_lshlrev_b32_e32 v0, 4, v14
	v_lshrrev_b32_e32 v2, 22, v2
	v_add_u32_e32 v2, v0, v2
	v_and_b32_e32 v2, 0xfffffc00, v2
	v_sub_u32_e32 v0, v0, v2
	v_lshrrev_b32_e32 v2, 4, v0
	v_bitop3_b32 v2, v2, v0, 32 bitop3:0x6c
	v_ashrrev_i32_e32 v0, 31, v0
	v_lshrrev_b32_e32 v0, 26, v0
	v_add_u32_e32 v0, v2, v0
	v_lshlrev_b32_e32 v3, 3, v15
	v_ashrrev_i32_e32 v17, 6, v0
	v_and_b32_e32 v16, -16, v3
	v_mul_i32_i24_e32 v3, 64, v17
	v_sub_u32_e32 v2, v2, v3
	v_add_u32_e32 v133, v17, v16
	v_ashrrev_i16_sdwa v2, v220, sext(v2) dst_sel:DWORD dst_unused:UNUSED_PAD src0_sel:DWORD src1_sel:BYTE_0
	s_ashr_i32 s10, s14, 6
	v_lshlrev_b32_e32 v0, 5, v15
	v_bfe_i32 v18, v2, 0, 16
	v_lshlrev_b32_e32 v2, 1, v133
	v_lshrrev_b32_e32 v3, 2, v133
	v_and_b32_e32 v4, 3, v17
	s_movk_i32 s8, 0xffe0
	v_writelane_b32 v254, s75, 3
	v_and_b32_e32 v0, 32, v0
	v_and_b32_e32 v2, 24, v2
	v_and_b32_e32 v3, 4, v3
	v_and_or_b32 v4, v133, s8, v4
	s_lshl_b32 s75, s10, 10
	v_or3_b32 v135, v4, v3, v2
	v_add_lshl_u32 v132, v0, v18, 1
	s_add_i32 s76, s75, 0
	v_mad_u64_u32 v[8:9], s[8:9], s40, v135, v[132:133]
	s_add_i32 m0, s76, 0x10000
	s_ashr_i32 s11, s14, 8
	global_load_lds_dwordx4 v8, s[6:7]
	s_add_i32 m0, s76, 0x12000
	s_lshl_b32 s8, s40, 7
	v_lshl_add_u32 v0, s40, 6, v8
	s_add_u32 s8, s6, s8
	global_load_lds_dwordx4 v0, s[6:7]
	s_addc_u32 s9, s7, 0
	s_add_i32 m0, s76, 0x14000
	v_mov_b32_e32 v9, v1
	s_add_i32 m0, s76, 0x16000
	v_lshl_add_u64 v[2:3], s[6:7], 0, v[8:9]
	v_lshl_add_u64 v[4:5], s[8:9], 0, v[8:9]
	v_lshl_add_u64 v[8:9], s[8:9], 0, v[0:1]
	v_mad_u64_u32 v[20:21], s[8:9], s17, v133, v[132:133]
	s_add_i32 s77, s76, 0x2000
	s_lshl_b32 s8, s17, 7
	s_mov_b32 m0, s76
	s_add_u32 s8, s4, s8
	v_lshl_add_u64 v[6:7], s[6:7], 0, v[0:1]
	global_load_lds_dwordx4 v20, s[4:5]
	v_lshl_add_u32 v0, s17, 6, v20
	s_mov_b32 m0, s77
	s_addc_u32 s9, s5, 0
	s_add_i32 s78, s76, 0x4000
	global_load_lds_dwordx4 v0, s[4:5]
	s_mov_b32 m0, s78
	s_add_i32 s79, s76, 0x6000
	global_load_lds_dwordx4 v20, s[8:9]
	s_mov_b32 m0, s79
	v_writelane_b32 v254, s84, 5
	global_load_lds_dwordx4 v0, s[8:9]
	v_mov_b32_e32 v21, v1
	s_cmp_eq_u32 s11, 1
	v_writelane_b32 v255, s21, 31
	s_mov_b32 s73, s20
	v_writelane_b32 v254, s85, 6
	v_lshl_add_u64 v[10:11], s[4:5], 0, v[20:21]
	v_lshl_add_u64 v[12:13], s[4:5], 0, v[0:1]
	s_cselect_b64 s[8:9], -1, 0
	s_cmp_lg_u32 s11, 1
	s_cbranch_scc1 .LBB0_854
	s_barrier
.LBB0_854:
	v_bfe_u32 v139, v14, 4, 2
	s_lshl_b32 s10, s10, 5
	v_and_b32_e32 v138, 15, v14
	v_lshlrev_b32_e32 v0, 4, v139
	v_lshlrev_b32_e32 v14, 2, v14
	s_and_b32 s81, s10, 0x60
	s_lshl_b32 s80, s11, 6
	v_lshl_or_b32 v0, v138, 6, v0
	s_lshl_b32 s11, s11, 13
	v_and_b32_e32 v14, 32, v14
	s_lshl_b32 s10, s81, 7
	v_bitop3_b32 v19, v0, s11, v14 bitop3:0xde
	v_bitop3_b32 v140, v0, s10, v14 bitop3:0xde
	s_mov_b64 s[10:11], 0x80
	v_lshl_add_u64 v[2:3], v[2:3], 0, s[10:11]
	s_add_i32 m0, s76, 0x18000
	s_waitcnt vmcnt(2)
	s_barrier
	global_load_lds_dwordx4 v[2:3], off
	v_lshl_add_u64 v[2:3], v[6:7], 0, s[10:11]
	s_add_i32 m0, s76, 0x1a000
	s_add_i32 s82, s76, 0x8000
	global_load_lds_dwordx4 v[2:3], off
	v_lshl_add_u64 v[2:3], v[10:11], 0, s[10:11]
	s_mov_b32 m0, s82
	s_add_i32 s83, s76, 0xa000
	global_load_lds_dwordx4 v[2:3], off
	v_lshl_add_u64 v[2:3], v[12:13], 0, s[10:11]
	s_mov_b32 m0, s83
	v_readlane_b32 s46, v253, 29
	global_load_lds_dwordx4 v[2:3], off
	v_lshl_add_u64 v[2:3], v[4:5], 0, s[10:11]
	s_add_i32 m0, s76, 0x1c000
	v_readlane_b32 s47, v253, 30
	v_lshl_add_u64 v[2:3], v[8:9], 0, s[10:11]
	s_add_i32 m0, s76, 0x1e000
	s_cmpk_lt_u32 s14, 0x100
	s_mul_i32 s10, s19, 0x2600000
	s_cselect_b64 s[12:13], -1, 0
	s_ashr_i32 s11, s10, 31
	s_add_u32 s14, s46, s10
	s_addc_u32 s15, s47, s11
	s_add_u32 s10, s14, 0x1680000
	v_readlane_b32 s36, v253, 25
	v_writelane_b32 v255, s10, 41
	s_addc_u32 s10, s15, 0
	s_mul_i32 s26, s36, 0x180000
	s_mul_hi_i32 s27, s36, 0x180000
	s_add_u32 s34, s46, s26
	s_addc_u32 s35, s47, s27
	v_writelane_b32 v255, s10, 27
	s_add_u32 s10, s34, 0x15140000
	s_addc_u32 s11, s35, 0
	v_writelane_b32 v255, s10, 39
	s_mov_b32 s28, s19
	v_readlane_b32 s37, v253, 26
	v_writelane_b32 v255, s11, 40
	v_readlane_b32 s10, v253, 22
	v_readlane_b32 s11, v253, 23
	s_mov_b32 s30, s10
	s_ashr_i32 s31, s10, 31
	s_lshl_b64 s[10:11], s[30:31], 18
	s_add_u32 s10, s14, s10
	s_addc_u32 s11, s15, s11
	s_add_u32 s10, s10, 0x1580000
	s_addc_u32 s11, s11, 0
	v_writelane_b32 v255, s10, 29
	s_cmp_lt_i32 s30, 4
	s_cselect_b64 s[18:19], -1, 0
	v_writelane_b32 v255, s11, 30
	s_lshl_b64 s[10:11], s[30:31], 19
	s_add_u32 s10, s14, s10
	s_addc_u32 s11, s15, s11
	s_add_u32 s20, s10, 0x1280000
	s_addc_u32 s21, s11, 0
	s_add_u32 s22, s34, 0x15080000
	s_addc_u32 s23, s35, 0
	s_add_u32 s24, s10, 0x1080000
	s_addc_u32 s25, s11, 0
	s_add_u32 s86, s46, 0x15000000
	s_addc_u32 s87, s47, 0
	s_add_u32 s26, s86, s26
	s_addc_u32 s27, s87, s27
	s_add_u32 s10, s10, 0xe80000
	v_writelane_b32 v253, s10, 37
	s_addc_u32 s10, s11, 0
	v_writelane_b32 v254, s28, 1
	v_writelane_b32 v253, s10, 22
	v_readlane_b32 s10, v254, 3
	s_or_b32 s10, s10, s28
	s_cmp_eq_u32 s10, 0
	s_movk_i32 s10, 0x6c0
	s_cselect_b32 s28, 0x700, s10
	v_readlane_b32 s10, v252, 39
	s_lshr_b32 s90, s28, 3
	v_readlane_b32 s11, v252, 40
	s_add_u32 s10, s14, 0x100000
	s_mov_b32 s29, s11
	v_writelane_b32 v255, s10, 33
	s_addc_u32 s10, s15, 0
	s_mul_i32 s11, s30, 0x160000
	v_writelane_b32 v255, s10, 57
	s_mul_hi_i32 s10, s30, 0x160000
	s_add_u32 s11, s14, s11
	s_addc_u32 s10, s15, s10
	s_mov_b32 s72, s30
	s_add_u32 s30, s11, 0x2180000
	s_addc_u32 s31, s10, 0
	s_mul_i32 s11, s36, 0xffea0000
	s_mul_hi_i32 s10, s36, 0xffea0000
	s_add_u32 s14, s26, s11
	s_addc_u32 s15, s27, s10
	s_lshl_b64 s[10:11], s[36:37], 18
	s_sub_u32 s10, 0, s10
	s_subb_u32 s11, 0, s11
	s_add_u32 s10, s34, s10
	s_addc_u32 s11, s35, s11
	s_add_u32 s36, s10, 0x15100000
	s_addc_u32 s37, s11, 0
	s_sub_u32 s2, 0, s2
	s_subb_u32 s3, 0, s3
	s_add_u32 s38, s22, s2
	s_addc_u32 s39, s23, s3
	v_writelane_b32 v255, s14, 59
	s_add_u32 s2, s46, 0xf000000
	s_addc_u32 s3, s47, 0
	v_writelane_b32 v255, s15, 60
	v_writelane_b32 v255, s2, 63
	v_and_b32_e32 v0, 1, v15
	v_lshlrev_b32_e32 v2, 1, v18
	v_writelane_b32 v254, s3, 0
	s_add_u32 s2, s46, 0x7800000
	s_addc_u32 s3, s47, 0
	s_add_u32 s93, s46, 0x5400000
	s_waitcnt vmcnt(4)
	s_addc_u32 s94, s47, 0
	v_lshl_add_u32 v134, v0, 6, v2
	v_mov_b32_e32 v2, v1
	v_mov_b32_e32 v3, v1
	v_writelane_b32 v255, s2, 61
	s_add_u32 s95, s46, 0x5000000
	v_add3_u32 v141, v17, v16, 64
	v_mov_b32_e32 v0, v1
	v_add_u32_e32 v142, 0, v19
	v_mov_b64_e32 v[6:7], v[2:3]
	v_mov_b64_e32 v[10:11], v[2:3]
	v_mov_b64_e32 v[14:15], v[2:3]
	v_mov_b64_e32 v[18:19], v[2:3]
	v_mov_b64_e32 v[22:23], v[2:3]
	v_mov_b64_e32 v[26:27], v[2:3]
	v_mov_b64_e32 v[30:31], v[2:3]
	v_mov_b64_e32 v[34:35], v[2:3]
	v_mov_b64_e32 v[38:39], v[2:3]
	v_mov_b64_e32 v[42:43], v[2:3]
	v_mov_b64_e32 v[46:47], v[2:3]
	v_mov_b64_e32 v[50:51], v[2:3]
	v_mov_b64_e32 v[54:55], v[2:3]
	v_mov_b64_e32 v[58:59], v[2:3]
	v_mov_b64_e32 v[62:63], v[2:3]
	v_mov_b64_e32 v[66:67], v[2:3]
	v_mov_b64_e32 v[70:71], v[2:3]
	v_mov_b64_e32 v[74:75], v[2:3]
	v_mov_b64_e32 v[78:79], v[2:3]
	v_mov_b64_e32 v[82:83], v[2:3]
	v_mov_b64_e32 v[86:87], v[2:3]
	v_mov_b64_e32 v[90:91], v[2:3]
	v_mov_b64_e32 v[94:95], v[2:3]
	v_mov_b64_e32 v[98:99], v[2:3]
	v_mov_b64_e32 v[102:103], v[2:3]
	v_mov_b64_e32 v[106:107], v[2:3]
	v_mov_b64_e32 v[110:111], v[2:3]
	v_mov_b64_e32 v[114:115], v[2:3]
	v_mov_b64_e32 v[118:119], v[2:3]
	v_mov_b64_e32 v[122:123], v[2:3]
	v_mov_b64_e32 v[126:127], v[2:3]
	v_mov_b64_e32 v[130:131], v[2:3]
	s_mov_b32 s84, 0
	v_writelane_b32 v255, s3, 62
	s_addc_u32 s96, s47, 0
	v_mov_b64_e32 v[4:5], v[0:1]
	v_mov_b64_e32 v[8:9], v[0:1]
	v_mov_b64_e32 v[12:13], v[0:1]
	v_mov_b64_e32 v[16:17], v[0:1]
	v_mov_b64_e32 v[20:21], v[0:1]
	v_mov_b64_e32 v[24:25], v[0:1]
	v_mov_b64_e32 v[28:29], v[0:1]
	v_mov_b64_e32 v[32:33], v[0:1]
	v_mov_b64_e32 v[36:37], v[0:1]
	v_mov_b64_e32 v[40:41], v[0:1]
	v_mov_b64_e32 v[44:45], v[0:1]
	v_mov_b64_e32 v[48:49], v[0:1]
	v_mov_b64_e32 v[52:53], v[0:1]
	v_mov_b64_e32 v[56:57], v[0:1]
	v_mov_b64_e32 v[60:61], v[0:1]
	v_mov_b64_e32 v[64:65], v[0:1]
	v_mov_b64_e32 v[68:69], v[0:1]
	v_mov_b64_e32 v[72:73], v[0:1]
	v_mov_b64_e32 v[76:77], v[0:1]
	v_mov_b64_e32 v[80:81], v[0:1]
	v_mov_b64_e32 v[84:85], v[0:1]
	v_mov_b64_e32 v[88:89], v[0:1]
	v_mov_b64_e32 v[92:93], v[0:1]
	v_mov_b64_e32 v[96:97], v[0:1]
	v_mov_b64_e32 v[100:101], v[0:1]
	v_mov_b64_e32 v[104:105], v[0:1]
	v_mov_b64_e32 v[108:109], v[0:1]
	v_mov_b64_e32 v[112:113], v[0:1]
	v_mov_b64_e32 v[116:117], v[0:1]
	v_mov_b64_e32 v[120:121], v[0:1]
	v_mov_b64_e32 v[124:125], v[0:1]
	v_mov_b64_e32 v[128:129], v[0:1]
	s_barrier
	s_branch .LBB0_857

.LBB0_913:
	s_add_i32 s35, s64, 2
	s_add_u32 s66, s62, 0x80
	s_addc_u32 s65, s63, 0
	s_add_i32 s67, 0, 0x10000
	s_add_i32 s88, 0, 0x14000
	v_add_u32_e32 v0, s67, v140
	ds_read_b128 v[144:147], v0
	ds_read_b128 v[148:151], v0 offset:1024
	ds_read_b128 v[152:155], v0 offset:2048
	ds_read_b128 v[156:159], v0 offset:3072
	v_add_u32_e32 v0, s88, v140
	s_cmp_eq_u32 s10, s64
	s_cselect_b32 s64, s60, s66
	s_cselect_b32 s65, s61, s65
	s_cselect_b32 s66, s74, s17
	s_cselect_b32 s69, s59, s15
	s_cselect_b32 s68, s58, s11
	s_cselect_b32 s89, s41, s40
	v_lshl_add_u64 v[208:209], s[62:63], 0, v[136:137]
	s_add_i32 m0, s76, 0xc000
	ds_read_b128 v[176:179], v142
	ds_read_b128 v[180:183], v142 offset:1024
	ds_read_b128 v[184:187], v142 offset:2048
	ds_read_b128 v[188:191], v142 offset:3072
	ds_read_b128 v[192:195], v142 offset:4096
	ds_read_b128 v[196:199], v142 offset:5120
	ds_read_b128 v[200:203], v142 offset:6144
	ds_read_b128 v[204:207], v142 offset:7168
	global_load_lds_dwordx4 v[208:209], off
	v_lshl_add_u64 v[208:209], s[62:63], 0, v[2:3]
	s_add_i32 m0, s76, 0xe000
	s_nop 0
	global_load_lds_dwordx4 v[208:209], off
	s_waitcnt vmcnt(6)
	s_waitcnt lgkmcnt(0)
	s_barrier
	s_setprio 1
	v_mfma_f32_16x16x32_bf16 v[128:131], v[144:147], v[176:179], v[128:131]
	v_mfma_f32_16x16x32_bf16 v[124:127], v[152:155], v[176:179], v[124:127]
	v_mfma_f32_16x16x32_bf16 v[120:123], v[144:147], v[184:187], v[120:123]
	v_mfma_f32_16x16x32_bf16 v[116:119], v[152:155], v[184:187], v[116:119]
	v_mfma_f32_16x16x32_bf16 v[112:115], v[144:147], v[192:195], v[112:115]
	v_mfma_f32_16x16x32_bf16 v[108:111], v[152:155], v[192:195], v[108:111]
	v_mfma_f32_16x16x32_bf16 v[104:107], v[144:147], v[200:203], v[104:107]
	v_mfma_f32_16x16x32_bf16 v[100:103], v[152:155], v[200:203], v[100:103]
	v_mfma_f32_16x16x32_bf16 v[128:131], v[148:151], v[180:183], v[128:131]
	v_mfma_f32_16x16x32_bf16 v[124:127], v[156:159], v[180:183], v[124:127]
	v_mfma_f32_16x16x32_bf16 v[120:123], v[148:151], v[188:191], v[120:123]
	v_mfma_f32_16x16x32_bf16 v[116:119], v[156:159], v[188:191], v[116:119]
	v_mfma_f32_16x16x32_bf16 v[112:115], v[148:151], v[196:199], v[112:115]
	v_mfma_f32_16x16x32_bf16 v[108:111], v[156:159], v[196:199], v[108:111]
	v_mfma_f32_16x16x32_bf16 v[104:107], v[148:151], v[204:207], v[104:107]
	v_mfma_f32_16x16x32_bf16 v[100:103], v[156:159], v[204:207], v[100:103]
	s_setprio 0
	s_barrier
	s_add_i32 s67, s67, s75
	v_mad_u64_u32 v[208:209], s[70:71], s89, v135, v[132:133]
	s_mov_b32 m0, s67
	ds_read_b128 v[176:179], v142 offset:16384
	ds_read_b128 v[180:183], v142 offset:17408
	ds_read_b128 v[184:187], v142 offset:18432
	ds_read_b128 v[188:191], v142 offset:19456
	ds_read_b128 v[192:195], v142 offset:20480
	ds_read_b128 v[196:199], v142 offset:21504
	ds_read_b128 v[200:203], v142 offset:22528
	ds_read_b128 v[204:207], v142 offset:23552
	v_mov_b32_e32 v209, v1
	global_load_lds_dwordx4 v208, s[68:69]
	v_lshl_add_u32 v0, s89, 6, v208
	s_add_i32 m0, s67, 0x2000
	s_lshl_b32 s67, s89, 7
	v_lshl_add_u64 v[210:211], s[68:69], 0, v[208:209]
	v_lshl_add_u64 v[212:213], s[68:69], 0, v[0:1]
	global_load_lds_dwordx4 v0, s[68:69]
	s_add_u32 s68, s68, s67
	s_addc_u32 s69, s69, 0
	s_add_i32 s67, s88, s75
	s_mov_b32 m0, s67
	v_lshl_add_u64 v[214:215], s[68:69], 0, v[208:209]
	s_add_i32 m0, s67, 0x2000
	v_lshl_add_u64 v[208:209], s[68:69], 0, v[0:1]
	v_mad_u64_u32 v[236:237], s[68:69], s66, v133, v[132:133]
	s_mov_b32 m0, s76
	v_lshl_add_u32 v0, s66, 6, v236
	global_load_lds_dwordx4 v236, s[64:65]
	s_mov_b32 m0, s77
	v_mov_b32_e32 v237, v1
	global_load_lds_dwordx4 v0, s[64:65]
	s_waitcnt vmcnt(6)
	s_waitcnt lgkmcnt(0)
	v_lshl_add_u64 v[238:239], s[64:65], 0, v[236:237]
	v_lshl_add_u64 v[244:245], s[64:65], 0, v[0:1]
	s_barrier
	s_setprio 1
	v_mfma_f32_16x16x32_bf16 v[64:67], v[144:147], v[176:179], v[64:67]
	v_mfma_f32_16x16x32_bf16 v[60:63], v[152:155], v[176:179], v[60:63]
	v_mfma_f32_16x16x32_bf16 v[56:59], v[144:147], v[184:187], v[56:59]
	v_mfma_f32_16x16x32_bf16 v[52:55], v[152:155], v[184:187], v[52:55]
	v_mfma_f32_16x16x32_bf16 v[48:51], v[144:147], v[192:195], v[48:51]
	v_mfma_f32_16x16x32_bf16 v[44:47], v[152:155], v[192:195], v[44:47]
	v_mfma_f32_16x16x32_bf16 v[40:43], v[144:147], v[200:203], v[40:43]
	v_mfma_f32_16x16x32_bf16 v[36:39], v[152:155], v[200:203], v[36:39]
	v_mfma_f32_16x16x32_bf16 v[64:67], v[148:151], v[180:183], v[64:67]
	v_mfma_f32_16x16x32_bf16 v[60:63], v[156:159], v[180:183], v[60:63]
	v_mfma_f32_16x16x32_bf16 v[56:59], v[148:151], v[188:191], v[56:59]
	v_mfma_f32_16x16x32_bf16 v[52:55], v[156:159], v[188:191], v[52:55]
	v_mfma_f32_16x16x32_bf16 v[48:51], v[148:151], v[196:199], v[48:51]
	v_mfma_f32_16x16x32_bf16 v[44:47], v[156:159], v[196:199], v[44:47]
	v_mfma_f32_16x16x32_bf16 v[40:43], v[148:151], v[204:207], v[40:43]
	v_mfma_f32_16x16x32_bf16 v[36:39], v[156:159], v[204:207], v[36:39]
	s_setprio 0
	s_barrier
	s_add_i32 s67, 0, 0x18000
	v_add_u32_e32 v143, s67, v140
	s_add_i32 s68, 0, 0x1c000
	ds_read_b128 v[144:147], v143
	ds_read_b128 v[148:151], v143 offset:1024
	ds_read_b128 v[152:155], v143 offset:2048
	ds_read_b128 v[156:159], v143 offset:3072
	v_add_u32_e32 v143, s68, v140
	s_lshl_b32 s66, s66, 7
	s_add_u32 s64, s64, s66
	s_addc_u32 s65, s65, 0
	s_mov_b32 m0, s78
	ds_read_b128 v[176:179], v142 offset:32768
	ds_read_b128 v[180:183], v142 offset:33792
	ds_read_b128 v[184:187], v142 offset:34816
	ds_read_b128 v[188:191], v142 offset:35840
	ds_read_b128 v[192:195], v142 offset:36864
	ds_read_b128 v[196:199], v142 offset:37888
	ds_read_b128 v[200:203], v142 offset:38912
	ds_read_b128 v[204:207], v142 offset:39936
	global_load_lds_dwordx4 v236, s[64:65]
	s_mov_b32 m0, s79
	s_nop 0
	global_load_lds_dwordx4 v0, s[64:65]
	s_waitcnt vmcnt(6)
	s_waitcnt lgkmcnt(0)
	s_barrier
	s_setprio 1
	v_mfma_f32_16x16x32_bf16 v[128:131], v[144:147], v[176:179], v[128:131]
	v_mfma_f32_16x16x32_bf16 v[124:127], v[152:155], v[176:179], v[124:127]
	v_mfma_f32_16x16x32_bf16 v[120:123], v[144:147], v[184:187], v[120:123]
	v_mfma_f32_16x16x32_bf16 v[116:119], v[152:155], v[184:187], v[116:119]
	v_mfma_f32_16x16x32_bf16 v[112:115], v[144:147], v[192:195], v[112:115]
	v_mfma_f32_16x16x32_bf16 v[108:111], v[152:155], v[192:195], v[108:111]
	v_mfma_f32_16x16x32_bf16 v[104:107], v[144:147], v[200:203], v[104:107]
	v_mfma_f32_16x16x32_bf16 v[100:103], v[152:155], v[200:203], v[100:103]
	v_mfma_f32_16x16x32_bf16 v[128:131], v[148:151], v[180:183], v[128:131]
	v_mfma_f32_16x16x32_bf16 v[124:127], v[156:159], v[180:183], v[124:127]
	v_mfma_f32_16x16x32_bf16 v[120:123], v[148:151], v[188:191], v[120:123]
	v_mfma_f32_16x16x32_bf16 v[116:119], v[156:159], v[188:191], v[116:119]
	v_mfma_f32_16x16x32_bf16 v[112:115], v[148:151], v[196:199], v[112:115]
	v_mfma_f32_16x16x32_bf16 v[108:111], v[156:159], v[196:199], v[108:111]
	v_mfma_f32_16x16x32_bf16 v[104:107], v[148:151], v[204:207], v[104:107]
	v_mfma_f32_16x16x32_bf16 v[100:103], v[156:159], v[204:207], v[100:103]
	s_setprio 0
	s_barrier
	s_add_i32 s64, s67, s75
	v_lshl_add_u64 v[210:211], v[210:211], 0, s[42:43]
	s_mov_b32 m0, s64
	ds_read_b128 v[176:179], v142 offset:49152
	ds_read_b128 v[180:183], v142 offset:50176
	ds_read_b128 v[184:187], v142 offset:51200
	ds_read_b128 v[188:191], v142 offset:52224
	ds_read_b128 v[192:195], v142 offset:53248
	ds_read_b128 v[196:199], v142 offset:54272
	ds_read_b128 v[200:203], v142 offset:55296
	ds_read_b128 v[204:207], v142 offset:56320
	global_load_lds_dwordx4 v[210:211], off
	v_lshl_add_u64 v[210:211], v[212:213], 0, s[42:43]
	s_add_i32 m0, s64, 0x2000
	s_add_i32 s64, s68, s75
	global_load_lds_dwordx4 v[210:211], off
	v_lshl_add_u64 v[210:211], v[214:215], 0, s[42:43]
	s_mov_b32 m0, s64
	v_lshl_add_u64 v[208:209], v[208:209], 0, s[42:43]
	s_add_i32 m0, s64, 0x2000
	s_nop 0
	v_lshl_add_u64 v[208:209], v[238:239], 0, s[42:43]
	s_mov_b32 m0, s82
	s_nop 0
	global_load_lds_dwordx4 v[208:209], off
	v_lshl_add_u64 v[208:209], v[244:245], 0, s[42:43]
	s_mov_b32 m0, s83
	s_nop 0
	global_load_lds_dwordx4 v[208:209], off
	s_waitcnt vmcnt(6)
	s_waitcnt lgkmcnt(0)
	s_barrier
	s_setprio 1
	v_mfma_f32_16x16x32_bf16 v[64:67], v[144:147], v[176:179], v[64:67]
	v_mfma_f32_16x16x32_bf16 v[60:63], v[152:155], v[176:179], v[60:63]
	v_mfma_f32_16x16x32_bf16 v[56:59], v[144:147], v[184:187], v[56:59]
	v_mfma_f32_16x16x32_bf16 v[52:55], v[152:155], v[184:187], v[52:55]
	v_mfma_f32_16x16x32_bf16 v[48:51], v[144:147], v[192:195], v[48:51]
	v_mfma_f32_16x16x32_bf16 v[44:47], v[152:155], v[192:195], v[44:47]
	v_mfma_f32_16x16x32_bf16 v[40:43], v[144:147], v[200:203], v[40:43]
	v_mfma_f32_16x16x32_bf16 v[36:39], v[152:155], v[200:203], v[36:39]
	v_mfma_f32_16x16x32_bf16 v[64:67], v[148:151], v[180:183], v[64:67]
	v_mfma_f32_16x16x32_bf16 v[60:63], v[156:159], v[180:183], v[60:63]
	v_mfma_f32_16x16x32_bf16 v[56:59], v[148:151], v[188:191], v[56:59]
	v_mfma_f32_16x16x32_bf16 v[52:55], v[156:159], v[188:191], v[52:55]
	v_mfma_f32_16x16x32_bf16 v[48:51], v[148:151], v[196:199], v[48:51]
	v_mfma_f32_16x16x32_bf16 v[44:47], v[156:159], v[196:199], v[44:47]
	v_mfma_f32_16x16x32_bf16 v[40:43], v[148:151], v[204:207], v[40:43]
	v_mfma_f32_16x16x32_bf16 v[36:39], v[156:159], v[204:207], v[36:39]
	s_setprio 0
	s_barrier
	s_add_u32 s11, s11, 0x100
	s_addc_u32 s15, s15, 0
	s_add_u32 s62, s62, 0x100
	s_addc_u32 s63, s63, 0
	s_cmp_ge_i32 s35, s44
	s_mov_b32 s64, s35
	s_cbranch_scc0 .LBB0_913

.LBB0_982:
	v_mov_b32_e32 v0, v138
	v_mov_b32_e32 v2, v139
	s_lshl_b32 s10, s88, 8
	s_add_i32 s10, s10, s80
	s_lshl_b32 s54, s89, 7
	v_add_u32_e32 v0, s10, v0
	v_lshl_add_u32 v2, v2, 3, s81
	s_ashr_i32 s65, s64, 31
	s_ashr_i32 s55, s54, 31
	v_mad_i64_i32 v[136:137], s[10:11], v0, s64, 0
	s_cmp_eq_u32 s35, 1
	v_ashrrev_i32_e32 v3, 31, v2
	s_mov_b64 s[10:11], -1
	s_cbranch_scc1 .LBB0_985
	v_lshl_add_u64 v[164:165], v[136:137], 1, s[62:63]
	v_lshl_add_u64 v[164:165], s[54:55], 1, v[164:165]
	v_lshl_add_u64 v[164:165], v[2:3], 1, v[164:165]
	s_lshl_b64 s[68:69], s[64:65], 5
	v_mov_b32_e32 v0, 0xa0
	v_pk_mul_f32 v[144:145], v[128:129], s[66:67] op_sel_hi:[1,0]
	v_pk_mul_f32 v[146:147], v[130:131], s[66:67] op_sel_hi:[1,0]
	v_pk_mul_f32 v[148:149], v[124:125], s[66:67] op_sel_hi:[1,0]
	v_pk_mul_f32 v[150:151], v[126:127], s[66:67] op_sel_hi:[1,0]
	v_cvt_pk_bf16_f32 v144, v144, v145
	v_cvt_pk_bf16_f32 v145, v146, v147
	v_cvt_pk_bf16_f32 v146, v148, v149
	v_cvt_pk_bf16_f32 v147, v150, v151
	flat_store_dwordx4 v[164:165], v[144:147]
	v_lshl_add_u64 v[164:165], v[164:165], 0, s[68:69]
	v_pk_mul_f32 v[154:155], v[120:121], s[66:67] op_sel_hi:[1,0]
	v_pk_mul_f32 v[156:157], v[122:123], s[66:67] op_sel_hi:[1,0]
	v_pk_mul_f32 v[158:159], v[116:117], s[66:67] op_sel_hi:[1,0]
	v_pk_mul_f32 v[160:161], v[118:119], s[66:67] op_sel_hi:[1,0]
	v_cvt_pk_bf16_f32 v154, v154, v155
	v_cvt_pk_bf16_f32 v155, v156, v157
	v_cvt_pk_bf16_f32 v156, v158, v159
	v_cvt_pk_bf16_f32 v157, v160, v161
	flat_store_dwordx4 v[164:165], v[154:157]
	v_lshl_add_u64 v[164:165], v[164:165], 0, s[68:69]
	v_pk_mul_f32 v[144:145], v[112:113], s[66:67] op_sel_hi:[1,0]
	v_pk_mul_f32 v[146:147], v[114:115], s[66:67] op_sel_hi:[1,0]
	v_pk_mul_f32 v[148:149], v[108:109], s[66:67] op_sel_hi:[1,0]
	v_pk_mul_f32 v[150:151], v[110:111], s[66:67] op_sel_hi:[1,0]
	v_cvt_pk_bf16_f32 v144, v144, v145
	v_cvt_pk_bf16_f32 v145, v146, v147
	v_cvt_pk_bf16_f32 v146, v148, v149
	v_cvt_pk_bf16_f32 v147, v150, v151
	flat_store_dwordx4 v[164:165], v[144:147]
	v_lshl_add_u64 v[164:165], v[164:165], 0, s[68:69]
	v_pk_mul_f32 v[154:155], v[104:105], s[66:67] op_sel_hi:[1,0]
	v_pk_mul_f32 v[156:157], v[106:107], s[66:67] op_sel_hi:[1,0]
	v_pk_mul_f32 v[158:159], v[100:101], s[66:67] op_sel_hi:[1,0]
	v_pk_mul_f32 v[160:161], v[102:103], s[66:67] op_sel_hi:[1,0]
	v_cvt_pk_bf16_f32 v154, v154, v155
	v_cvt_pk_bf16_f32 v155, v156, v157
	v_cvt_pk_bf16_f32 v156, v158, v159
	v_cvt_pk_bf16_f32 v157, v160, v161
	flat_store_dwordx4 v[164:165], v[154:157]
	v_mad_i64_i32 v[164:165], s[10:11], s64, v0, v[164:165]
	v_pk_mul_f32 v[144:145], v[64:65], s[66:67] op_sel_hi:[1,0]
	v_pk_mul_f32 v[146:147], v[66:67], s[66:67] op_sel_hi:[1,0]
	v_pk_mul_f32 v[148:149], v[60:61], s[66:67] op_sel_hi:[1,0]
	v_pk_mul_f32 v[150:151], v[62:63], s[66:67] op_sel_hi:[1,0]
	v_cvt_pk_bf16_f32 v144, v144, v145
	v_cvt_pk_bf16_f32 v145, v146, v147
	v_cvt_pk_bf16_f32 v146, v148, v149
	v_cvt_pk_bf16_f32 v147, v150, v151
	flat_store_dwordx4 v[164:165], v[144:147]
	v_lshl_add_u64 v[164:165], v[164:165], 0, s[68:69]
	v_pk_mul_f32 v[154:155], v[56:57], s[66:67] op_sel_hi:[1,0]
	v_pk_mul_f32 v[156:157], v[58:59], s[66:67] op_sel_hi:[1,0]
	v_pk_mul_f32 v[158:159], v[52:53], s[66:67] op_sel_hi:[1,0]
	v_pk_mul_f32 v[160:161], v[54:55], s[66:67] op_sel_hi:[1,0]
	v_cvt_pk_bf16_f32 v154, v154, v155
	v_cvt_pk_bf16_f32 v155, v156, v157
	v_cvt_pk_bf16_f32 v156, v158, v159
	v_cvt_pk_bf16_f32 v157, v160, v161
	flat_store_dwordx4 v[164:165], v[154:157]
	v_lshl_add_u64 v[164:165], v[164:165], 0, s[68:69]
	v_pk_mul_f32 v[144:145], v[48:49], s[66:67] op_sel_hi:[1,0]
	v_pk_mul_f32 v[146:147], v[50:51], s[66:67] op_sel_hi:[1,0]
	v_pk_mul_f32 v[148:149], v[44:45], s[66:67] op_sel_hi:[1,0]
	v_pk_mul_f32 v[150:151], v[46:47], s[66:67] op_sel_hi:[1,0]
	v_cvt_pk_bf16_f32 v144, v144, v145
	v_cvt_pk_bf16_f32 v145, v146, v147
	v_cvt_pk_bf16_f32 v146, v148, v149
	v_cvt_pk_bf16_f32 v147, v150, v151
	flat_store_dwordx4 v[164:165], v[144:147]
	v_lshl_add_u64 v[164:165], v[164:165], 0, s[68:69]
	v_pk_mul_f32 v[154:155], v[40:41], s[66:67] op_sel_hi:[1,0]
	v_pk_mul_f32 v[156:157], v[42:43], s[66:67] op_sel_hi:[1,0]
	v_pk_mul_f32 v[158:159], v[36:37], s[66:67] op_sel_hi:[1,0]
	v_pk_mul_f32 v[160:161], v[38:39], s[66:67] op_sel_hi:[1,0]
	v_cvt_pk_bf16_f32 v154, v154, v155
	v_cvt_pk_bf16_f32 v155, v156, v157
	v_cvt_pk_bf16_f32 v156, v158, v159
	v_cvt_pk_bf16_f32 v157, v160, v161
	flat_store_dwordx4 v[164:165], v[154:157]
	s_cbranch_execz .LBB0_986
